# static priority: one s_setprio 1 at entry for workgroups 256..511 (on top of the combined version)
# baseline (speedup 1.0000x reference)
; __global__ void __launch_bounds__(256, 2) mega(Params p_in, int ph_begin, int ph_end) {
;   __shared__ __attribute__((aligned(16))) unsigned char smem[74752];
;   __shared__ int s_item;
;   __shared__ uint4 xb_words;
;   if (ph_begin == 0x7fffffff) cg::this_grid().sync();
;   int ph = 0;
;   unsigned* xbar = (unsigned*)(p_in.ws + OFF_BAR);
;   if (threadIdx.x == 0) xb_words = make_uint4(0u, 0u, 0u, 0u);
;   __syncthreads();
_Z4mega6Paramsii:
	v_writelane_b32 v254, s2, 0
	s_cmpk_lt_u32 s2, 0x100
	s_cbranch_scc1 .Lprio_skip
	s_setprio 1
.Lprio_skip:
	s_load_dword s2, s[0:1], 0xb0
	s_load_dwordx4 s[68:71], s[0:1], 0xa0
	s_load_dwordx8 s[4:11], s[0:1], 0x80
	s_waitcnt lgkmcnt(0)
	s_cmp_eq_u32 s2, 0x7fffffff
	v_writelane_b32 v254, s4, 1
	s_nop 1
	v_writelane_b32 v254, s5, 2
	v_writelane_b32 v254, s6, 3
	v_writelane_b32 v254, s7, 4
	v_writelane_b32 v254, s8, 5
	v_writelane_b32 v254, s9, 6
	v_writelane_b32 v254, s10, 7
	v_writelane_b32 v254, s11, 8
	s_cbranch_scc1 .LBB0_2
	v_and_b32_e32 v242, 0x3ff, v0
	s_cbranch_execz .LBB0_3
	s_branch .LBB0_14
